# snsa score loop: 16-lane reduce via DPP moves instead of five ds_bpermute round trips per key
# speedup vs baseline: 1.0421x; 1.0001x over previous
; DI int rel_bucket(int d) {
;     if (d < 16) return d < 0 ? 0 : d;
;     int b = 16;
;     b += (d >= 21) + (d >= 27) + (d >= 35) + (d >= 46) + (d >= 59) + (d >= 77) + (d >= 99) + (d >= 128) + (d >= 166) + (d >= 216) + (d >= 280) + (d >= 363) + (d >= 470) + (d >= 609) + (d >= 790);
;     return b;
; }
; DI void snsa_unit(const Args& a, LAS unsigned char* lds, int s, int g) {
;     ...
;             for (int u = 0; u < 8; ++u) { const int kk = k0 + 32 * u;
;                 float p0 = x[u].x * q4[0].x + x[u].y * q4[0].y + x[u].z * q4[0].z + x[u].w * q4[0].w, p1 = x[u].x * q4[1].x + x[u].y * q4[1].y + x[u].z * q4[1].z + x[u].w * q4[1].w;
;                 float p2 = x[u].x * q4[2].x + x[u].y * q4[2].y + x[u].z * q4[2].z + x[u].w * q4[2].w, p3 = x[u].x * q4[3].x + x[u].y * q4[3].y + x[u].z * q4[3].z + x[u].w * q4[3].w;
;                 const bool o1 = (c16 & 1) != 0, o2 = (c16 & 2) != 0;
;                 float ka = o1 ? p2 : p0, kb2 = o1 ? p3 : p1; const float sa = o1 ? p0 : p2, sb = o1 ? p1 : p3;
;                 ka += __shfl_xor(sa, 1); kb2 += __shfl_xor(sb, 1);
;                 float e = o2 ? kb2 : ka; const float f = o2 ? ka : kb2;
;                 e += __shfl_xor(f, 2); e += __shfl_xor(e, 4); e += __shfl_xor(e, 8);
;                 if (c16 < 4 && kk < nkeys) SC[myh * 1024 + kk] = valid[u] ? e + rbias[rel_bucket(dist[u]) * 8 + g * 4 + myh] * LOG2E : -INFINITY; }
.Lsnsa_sc_f32:
	v_mul_f32_e32 v14, v23, v39
	s_waitcnt lgkmcnt(0)
	v_mul_f32_e32 v15, v27, v39
	s_waitcnt lgkmcnt(1)
	v_mul_f32_e32 v16, v31, v39
	s_waitcnt lgkmcnt(0)
	v_mul_f32_e32 v17, v35, v39
	v_fmac_f32_e32 v14, v22, v38
	v_fmac_f32_e32 v15, v26, v38
	v_fmac_f32_e32 v16, v30, v38
	v_fmac_f32_e32 v17, v34, v38
	v_fmac_f32_e32 v14, v24, v40
	v_fmac_f32_e32 v15, v28, v40
	v_fmac_f32_e32 v16, v32, v40
	v_fmac_f32_e32 v17, v36, v40
	v_fmac_f32_e32 v14, v25, v41
	v_fmac_f32_e32 v15, v29, v41
	v_fmac_f32_e32 v16, v33, v41
	v_fmac_f32_e32 v17, v37, v41
	v_cndmask_b32_e64 v18, v14, v16, s[10:11]
	v_cndmask_b32_e64 v19, v15, v17, s[10:11]
	s_nop 1
	v_mov_b32_dpp v18, v18 quad_perm:[1,0,3,2] row_mask:0xf bank_mask:0xf
	s_nop 1
	v_mov_b32_dpp v19, v19 quad_perm:[1,0,3,2] row_mask:0xf bank_mask:0xf
	v_cndmask_b32_e64 v14, v16, v14, s[10:11]
	v_cndmask_b32_e64 v15, v17, v15, s[10:11]
	s_waitcnt lgkmcnt(1)
	v_add_f32_e32 v14, v14, v18
	s_waitcnt lgkmcnt(0)
	v_add_f32_e32 v15, v15, v19
	v_cndmask_b32_e64 v16, v14, v15, s[12:13]
	s_nop 1
	v_mov_b32_dpp v16, v16 quad_perm:[2,3,0,1] row_mask:0xf bank_mask:0xf
	v_cndmask_b32_e64 v14, v15, v14, s[12:13]
	s_waitcnt lgkmcnt(0)
	v_add_f32_e32 v14, v14, v16
	s_nop 1
	v_mov_b32_dpp v15, v14 row_shl:4 row_mask:0xf bank_mask:0x5
	v_mov_b32_dpp v15, v14 row_shr:4 row_mask:0xf bank_mask:0xa
	s_waitcnt lgkmcnt(0)
	v_add_f32_e32 v14, v14, v15
	s_nop 1
	v_mov_b32_dpp v15, v14 row_ror:8 row_mask:0xf bank_mask:0xf
	s_and_saveexec_b64 s[24:25], s[14:15]
	s_cbranch_execz .LBB0_1569
	v_mov_b32_e32 v16, 0xff800000
	s_and_saveexec_b64 s[28:29], s[20:21]
	s_cbranch_execz .LBB0_1568
	v_cmp_lt_i32_e32 vcc, 15, v6
	s_and_saveexec_b64 s[82:83], vcc
	s_xor_b64 s[82:83], exec, s[82:83]
	s_cbranch_execz .LBB0_1565
	v_cmp_lt_u32_e32 vcc, 20, v6
	s_nop 1
	v_cndmask_b32_e64 v16, 0, 1, vcc
	v_cmp_lt_u32_e32 vcc, 45, v6
	s_nop 1
	v_cndmask_b32_e64 v17, 0, 1, vcc
	v_cmp_lt_u32_e32 vcc, s86, v6
	s_nop 1
	v_cndmask_b32_e64 v18, 0, 1, vcc
	v_cmp_lt_u32_e32 vcc, s88, v6
	s_nop 1
	v_cndmask_b32_e64 v19, 0, 1, vcc
	v_cmp_lt_u32_e32 vcc, s90, v6
	s_nop 1
	v_cndmask_b32_e64 v20, 0, 1, vcc
	v_cmp_lt_u32_e32 vcc, s92, v6
	s_nop 1
	v_cndmask_b32_e64 v21, 0, 1, vcc
	v_cmp_lt_u32_e32 vcc, s94, v6
	s_nop 1
	v_cndmask_b32_e64 v38, 0, 1, vcc
	v_cmp_lt_u32_e32 vcc, 26, v6
	s_nop 1
	v_cndmask_b32_e64 v39, 16, 17, vcc
	v_cmp_lt_u32_e32 vcc, 34, v6
	s_nop 1
	v_addc_co_u32_e32 v16, vcc, v39, v16, vcc
	v_cmp_lt_u32_e32 vcc, 58, v6
	s_nop 1
	v_addc_co_u32_e32 v16, vcc, v16, v17, vcc
	v_cmp_lt_u32_e32 vcc, s87, v6
	s_nop 1
	v_addc_co_u32_e32 v16, vcc, v16, v18, vcc
	v_cmp_lt_u32_e32 vcc, s89, v6
	s_nop 1
	v_addc_co_u32_e32 v16, vcc, v16, v19, vcc
	v_cmp_lt_u32_e32 vcc, s91, v6
	s_nop 1
	v_addc_co_u32_e32 v16, vcc, v16, v20, vcc
	v_cmp_lt_u32_e32 vcc, s93, v6
	s_nop 1
	v_addc_co_u32_e32 v16, vcc, v16, v21, vcc
	v_cmp_lt_u32_e32 vcc, s95, v6
	s_nop 1
	v_addc_co_u32_e32 v17, vcc, v16, v38, vcc

; DI int rel_bucket(int d) {
;     if (d < 16) return d < 0 ? 0 : d;
;     int b = 16;
;     b += (d >= 21) + (d >= 27) + (d >= 35) + (d >= 46) + (d >= 59) + (d >= 77) + (d >= 99) + (d >= 128) + (d >= 166) + (d >= 216) + (d >= 280) + (d >= 363) + (d >= 470) + (d >= 609) + (d >= 790);
;     return b;
; }
; DI void snsa_unit(const Args& a, LAS unsigned char* lds, int s, int g) {
;     ...
;             for (int u = 0; u < 8; ++u) { const int kk = k0 + 32 * u;
;                 float p0 = x[u].x * q4[0].x + x[u].y * q4[0].y + x[u].z * q4[0].z + x[u].w * q4[0].w, p1 = x[u].x * q4[1].x + x[u].y * q4[1].y + x[u].z * q4[1].z + x[u].w * q4[1].w;
;                 float p2 = x[u].x * q4[2].x + x[u].y * q4[2].y + x[u].z * q4[2].z + x[u].w * q4[2].w, p3 = x[u].x * q4[3].x + x[u].y * q4[3].y + x[u].z * q4[3].z + x[u].w * q4[3].w;
;                 const bool o1 = (c16 & 1) != 0, o2 = (c16 & 2) != 0;
;                 float ka = o1 ? p2 : p0, kb2 = o1 ? p3 : p1; const float sa = o1 ? p0 : p2, sb = o1 ? p1 : p3;
;                 ka += __shfl_xor(sa, 1); kb2 += __shfl_xor(sb, 1);
;                 float e = o2 ? kb2 : ka; const float f = o2 ? ka : kb2;
;                 e += __shfl_xor(f, 2); e += __shfl_xor(e, 4); e += __shfl_xor(e, 8);
;                 if (c16 < 4 && kk < nkeys) SC[myh * 1024 + kk] = valid[u] ? e + rbias[rel_bucket(dist[u]) * 8 + g * 4 + myh] * LOG2E : -INFINITY; }
.LBB0_1569:
	s_or_b64 exec, exec, s[24:25]
	v_mul_f32_e32 v6, v23, v43
	v_mul_f32_e32 v14, v27, v43
	s_waitcnt lgkmcnt(0)
	v_mul_f32_e32 v15, v31, v43
	v_mul_f32_e32 v16, v35, v43
	v_fmac_f32_e32 v6, v22, v42
	v_fmac_f32_e32 v14, v26, v42
	v_fmac_f32_e32 v15, v30, v42
	v_fmac_f32_e32 v16, v34, v42
	v_fmac_f32_e32 v6, v24, v44
	v_fmac_f32_e32 v14, v28, v44
	v_fmac_f32_e32 v15, v32, v44
	v_fmac_f32_e32 v16, v36, v44
	v_fmac_f32_e32 v6, v25, v45
	v_fmac_f32_e32 v14, v29, v45
	v_fmac_f32_e32 v15, v33, v45
	v_fmac_f32_e32 v16, v37, v45
	v_cndmask_b32_e64 v17, v6, v15, s[10:11]
	v_cndmask_b32_e64 v18, v14, v16, s[10:11]
	s_nop 1
	v_mov_b32_dpp v17, v17 quad_perm:[1,0,3,2] row_mask:0xf bank_mask:0xf
	s_nop 1
	v_mov_b32_dpp v18, v18 quad_perm:[1,0,3,2] row_mask:0xf bank_mask:0xf
	v_cndmask_b32_e64 v6, v15, v6, s[10:11]
	v_cndmask_b32_e64 v14, v16, v14, s[10:11]
	v_cmp_gt_i32_e32 vcc, s2, v124
	s_waitcnt lgkmcnt(1)
	v_add_f32_e32 v6, v6, v17
	s_waitcnt lgkmcnt(0)
	v_add_f32_e32 v14, v14, v18
	v_cndmask_b32_e64 v15, v6, v14, s[12:13]
	s_nop 1
	v_mov_b32_dpp v15, v15 quad_perm:[2,3,0,1] row_mask:0xf bank_mask:0xf
	v_cndmask_b32_e64 v6, v14, v6, s[12:13]
	s_and_b64 s[28:29], s[14:15], vcc
	s_waitcnt lgkmcnt(0)
	v_add_f32_e32 v6, v6, v15
	s_nop 1
	v_mov_b32_dpp v14, v6 row_shl:4 row_mask:0xf bank_mask:0x5
	v_mov_b32_dpp v14, v6 row_shr:4 row_mask:0xf bank_mask:0xa
	s_waitcnt lgkmcnt(0)
	v_add_f32_e32 v6, v6, v14
	s_nop 1
	v_mov_b32_dpp v14, v6 row_ror:8 row_mask:0xf bank_mask:0xf
	s_and_saveexec_b64 s[24:25], s[28:29]
	s_cbranch_execz .LBB0_1577
	v_mov_b32_e32 v15, 0xff800000
	s_and_saveexec_b64 s[28:29], s[58:59]
	s_cbranch_execz .LBB0_1576
	v_cmp_lt_i32_e32 vcc, 15, v7
	s_and_saveexec_b64 s[82:83], vcc
	s_xor_b64 s[82:83], exec, s[82:83]
	s_cbranch_execz .LBB0_1573
	v_cmp_lt_u32_e32 vcc, 20, v7
	s_nop 1
	v_cndmask_b32_e64 v15, 0, 1, vcc
	v_cmp_lt_u32_e32 vcc, 45, v7
	s_nop 1
	v_cndmask_b32_e64 v16, 0, 1, vcc
	v_cmp_lt_u32_e32 vcc, s86, v7
	s_nop 1
	v_cndmask_b32_e64 v17, 0, 1, vcc
	v_cmp_lt_u32_e32 vcc, s88, v7
	s_nop 1
	v_cndmask_b32_e64 v18, 0, 1, vcc
	v_cmp_lt_u32_e32 vcc, s90, v7
	s_nop 1
	v_cndmask_b32_e64 v19, 0, 1, vcc
	v_cmp_lt_u32_e32 vcc, s92, v7
	s_nop 1
	v_cndmask_b32_e64 v20, 0, 1, vcc
	v_cmp_lt_u32_e32 vcc, s94, v7
	s_nop 1
	v_cndmask_b32_e64 v21, 0, 1, vcc
	v_cmp_lt_u32_e32 vcc, 26, v7
	s_nop 1
	v_cndmask_b32_e64 v38, 16, 17, vcc
	v_cmp_lt_u32_e32 vcc, 34, v7
	s_nop 1
	v_addc_co_u32_e32 v15, vcc, v38, v15, vcc
	v_cmp_lt_u32_e32 vcc, 58, v7
	s_nop 1
	v_addc_co_u32_e32 v15, vcc, v15, v16, vcc
	v_cmp_lt_u32_e32 vcc, s87, v7
	s_nop 1
	v_addc_co_u32_e32 v15, vcc, v15, v17, vcc
	v_cmp_lt_u32_e32 vcc, s89, v7
	s_nop 1
	v_addc_co_u32_e32 v15, vcc, v15, v18, vcc
	v_cmp_lt_u32_e32 vcc, s91, v7
	s_nop 1
	v_addc_co_u32_e32 v15, vcc, v15, v19, vcc
	v_cmp_lt_u32_e32 vcc, s93, v7
	s_nop 1
	v_addc_co_u32_e32 v15, vcc, v15, v20, vcc
	v_cmp_lt_u32_e32 vcc, s95, v7
	s_nop 1
	v_addc_co_u32_e32 v16, vcc, v15, v21, vcc

; DI int rel_bucket(int d) {
;     if (d < 16) return d < 0 ? 0 : d;
;     int b = 16;
;     b += (d >= 21) + (d >= 27) + (d >= 35) + (d >= 46) + (d >= 59) + (d >= 77) + (d >= 99) + (d >= 128) + (d >= 166) + (d >= 216) + (d >= 280) + (d >= 363) + (d >= 470) + (d >= 609) + (d >= 790);
;     return b;
; }
; DI void snsa_unit(const Args& a, LAS unsigned char* lds, int s, int g) {
;     ...
;             for (int u = 0; u < 8; ++u) { const int kk = k0 + 32 * u;
;                 float p0 = x[u].x * q4[0].x + x[u].y * q4[0].y + x[u].z * q4[0].z + x[u].w * q4[0].w, p1 = x[u].x * q4[1].x + x[u].y * q4[1].y + x[u].z * q4[1].z + x[u].w * q4[1].w;
;                 float p2 = x[u].x * q4[2].x + x[u].y * q4[2].y + x[u].z * q4[2].z + x[u].w * q4[2].w, p3 = x[u].x * q4[3].x + x[u].y * q4[3].y + x[u].z * q4[3].z + x[u].w * q4[3].w;
;                 const bool o1 = (c16 & 1) != 0, o2 = (c16 & 2) != 0;
;                 float ka = o1 ? p2 : p0, kb2 = o1 ? p3 : p1; const float sa = o1 ? p0 : p2, sb = o1 ? p1 : p3;
;                 ka += __shfl_xor(sa, 1); kb2 += __shfl_xor(sb, 1);
;                 float e = o2 ? kb2 : ka; const float f = o2 ? ka : kb2;
;                 e += __shfl_xor(f, 2); e += __shfl_xor(e, 4); e += __shfl_xor(e, 8);
;                 if (c16 < 4 && kk < nkeys) SC[myh * 1024 + kk] = valid[u] ? e + rbias[rel_bucket(dist[u]) * 8 + g * 4 + myh] * LOG2E : -INFINITY; }
.LBB0_1577:
	s_or_b64 exec, exec, s[24:25]
	v_mul_f32_e32 v6, v23, v47
	v_mul_f32_e32 v7, v27, v47
	s_waitcnt lgkmcnt(0)
	v_mul_f32_e32 v14, v31, v47
	v_mul_f32_e32 v15, v35, v47
	v_fmac_f32_e32 v6, v22, v46
	v_fmac_f32_e32 v7, v26, v46
	v_fmac_f32_e32 v14, v30, v46
	v_fmac_f32_e32 v15, v34, v46
	v_fmac_f32_e32 v6, v24, v48
	v_fmac_f32_e32 v7, v28, v48
	v_fmac_f32_e32 v14, v32, v48
	v_fmac_f32_e32 v15, v36, v48
	v_fmac_f32_e32 v6, v25, v49
	v_fmac_f32_e32 v7, v29, v49
	v_fmac_f32_e32 v14, v33, v49
	v_fmac_f32_e32 v15, v37, v49
	v_cndmask_b32_e64 v16, v6, v14, s[10:11]
	v_cndmask_b32_e64 v17, v7, v15, s[10:11]
	s_nop 1
	v_mov_b32_dpp v16, v16 quad_perm:[1,0,3,2] row_mask:0xf bank_mask:0xf
	s_nop 1
	v_mov_b32_dpp v17, v17 quad_perm:[1,0,3,2] row_mask:0xf bank_mask:0xf
	v_cndmask_b32_e64 v6, v14, v6, s[10:11]
	v_cndmask_b32_e64 v7, v15, v7, s[10:11]
	v_cmp_gt_i32_e32 vcc, s2, v125
	s_waitcnt lgkmcnt(1)
	v_add_f32_e32 v6, v6, v16
	s_waitcnt lgkmcnt(0)
	v_add_f32_e32 v7, v7, v17
	v_cndmask_b32_e64 v14, v6, v7, s[12:13]
	s_nop 1
	v_mov_b32_dpp v14, v14 quad_perm:[2,3,0,1] row_mask:0xf bank_mask:0xf
	v_cndmask_b32_e64 v6, v7, v6, s[12:13]
	s_and_b64 s[28:29], s[14:15], vcc
	s_waitcnt lgkmcnt(0)
	v_add_f32_e32 v6, v6, v14
	s_nop 1
	v_mov_b32_dpp v7, v6 row_shl:4 row_mask:0xf bank_mask:0x5
	v_mov_b32_dpp v7, v6 row_shr:4 row_mask:0xf bank_mask:0xa
	s_waitcnt lgkmcnt(0)
	v_add_f32_e32 v6, v6, v7
	s_nop 1
	v_mov_b32_dpp v7, v6 row_ror:8 row_mask:0xf bank_mask:0xf
	s_and_saveexec_b64 s[24:25], s[28:29]
	s_cbranch_execz .LBB0_1585
	v_mov_b32_e32 v14, 0xff800000
	s_and_saveexec_b64 s[28:29], s[4:5]
	s_cbranch_execz .LBB0_1584
	v_cmp_lt_i32_e32 vcc, 15, v8
	s_and_saveexec_b64 s[82:83], vcc
	s_xor_b64 s[82:83], exec, s[82:83]
	s_cbranch_execz .LBB0_1581
	v_cmp_lt_u32_e32 vcc, 20, v8
	s_nop 1
	v_cndmask_b32_e64 v14, 0, 1, vcc
	v_cmp_lt_u32_e32 vcc, 45, v8
	s_nop 1
	v_cndmask_b32_e64 v15, 0, 1, vcc
	v_cmp_lt_u32_e32 vcc, s86, v8
	s_nop 1
	v_cndmask_b32_e64 v16, 0, 1, vcc
	v_cmp_lt_u32_e32 vcc, s88, v8
	s_nop 1
	v_cndmask_b32_e64 v17, 0, 1, vcc
	v_cmp_lt_u32_e32 vcc, s90, v8
	s_nop 1
	v_cndmask_b32_e64 v18, 0, 1, vcc
	v_cmp_lt_u32_e32 vcc, s92, v8
	s_nop 1
	v_cndmask_b32_e64 v19, 0, 1, vcc
	v_cmp_lt_u32_e32 vcc, s94, v8
	s_nop 1
	v_cndmask_b32_e64 v20, 0, 1, vcc
	v_cmp_lt_u32_e32 vcc, 26, v8
	s_nop 1
	v_cndmask_b32_e64 v21, 16, 17, vcc
	v_cmp_lt_u32_e32 vcc, 34, v8
	s_nop 1
	v_addc_co_u32_e32 v14, vcc, v21, v14, vcc
	v_cmp_lt_u32_e32 vcc, 58, v8
	s_nop 1
	v_addc_co_u32_e32 v14, vcc, v14, v15, vcc
	v_cmp_lt_u32_e32 vcc, s87, v8
	s_nop 1
	v_addc_co_u32_e32 v14, vcc, v14, v16, vcc
	v_cmp_lt_u32_e32 vcc, s89, v8
	s_nop 1
	v_addc_co_u32_e32 v14, vcc, v14, v17, vcc
	v_cmp_lt_u32_e32 vcc, s91, v8
	s_nop 1
	v_addc_co_u32_e32 v14, vcc, v14, v18, vcc
	v_cmp_lt_u32_e32 vcc, s93, v8
	s_nop 1
	v_addc_co_u32_e32 v14, vcc, v14, v19, vcc
	v_cmp_lt_u32_e32 vcc, s95, v8
	s_nop 1
	v_addc_co_u32_e32 v15, vcc, v14, v20, vcc

; DI int rel_bucket(int d) {
;     if (d < 16) return d < 0 ? 0 : d;
;     int b = 16;
;     b += (d >= 21) + (d >= 27) + (d >= 35) + (d >= 46) + (d >= 59) + (d >= 77) + (d >= 99) + (d >= 128) + (d >= 166) + (d >= 216) + (d >= 280) + (d >= 363) + (d >= 470) + (d >= 609) + (d >= 790);
;     return b;
; }
; DI void snsa_unit(const Args& a, LAS unsigned char* lds, int s, int g) {
;     ...
;             for (int u = 0; u < 8; ++u) { const int kk = k0 + 32 * u;
;                 float p0 = x[u].x * q4[0].x + x[u].y * q4[0].y + x[u].z * q4[0].z + x[u].w * q4[0].w, p1 = x[u].x * q4[1].x + x[u].y * q4[1].y + x[u].z * q4[1].z + x[u].w * q4[1].w;
;                 float p2 = x[u].x * q4[2].x + x[u].y * q4[2].y + x[u].z * q4[2].z + x[u].w * q4[2].w, p3 = x[u].x * q4[3].x + x[u].y * q4[3].y + x[u].z * q4[3].z + x[u].w * q4[3].w;
;                 const bool o1 = (c16 & 1) != 0, o2 = (c16 & 2) != 0;
;                 float ka = o1 ? p2 : p0, kb2 = o1 ? p3 : p1; const float sa = o1 ? p0 : p2, sb = o1 ? p1 : p3;
;                 ka += __shfl_xor(sa, 1); kb2 += __shfl_xor(sb, 1);
;                 float e = o2 ? kb2 : ka; const float f = o2 ? ka : kb2;
;                 e += __shfl_xor(f, 2); e += __shfl_xor(e, 4); e += __shfl_xor(e, 8);
;                 if (c16 < 4 && kk < nkeys) SC[myh * 1024 + kk] = valid[u] ? e + rbias[rel_bucket(dist[u]) * 8 + g * 4 + myh] * LOG2E : -INFINITY; }
.LBB0_1585:
	s_or_b64 exec, exec, s[24:25]
	v_mul_f32_e32 v6, v23, v51
	s_waitcnt lgkmcnt(0)
	v_mul_f32_e32 v7, v27, v51
	v_mul_f32_e32 v8, v31, v51
	v_mul_f32_e32 v14, v35, v51
	v_fmac_f32_e32 v6, v22, v50
	v_fmac_f32_e32 v7, v26, v50
	v_fmac_f32_e32 v8, v30, v50
	v_fmac_f32_e32 v14, v34, v50
	v_fmac_f32_e32 v6, v24, v52
	v_fmac_f32_e32 v7, v28, v52
	v_fmac_f32_e32 v8, v32, v52
	v_fmac_f32_e32 v14, v36, v52
	v_fmac_f32_e32 v6, v25, v53
	v_fmac_f32_e32 v7, v29, v53
	v_fmac_f32_e32 v8, v33, v53
	v_fmac_f32_e32 v14, v37, v53
	v_cndmask_b32_e64 v15, v6, v8, s[10:11]
	v_cndmask_b32_e64 v16, v7, v14, s[10:11]
	s_nop 1
	v_mov_b32_dpp v15, v15 quad_perm:[1,0,3,2] row_mask:0xf bank_mask:0xf
	s_nop 1
	v_mov_b32_dpp v16, v16 quad_perm:[1,0,3,2] row_mask:0xf bank_mask:0xf
	v_cndmask_b32_e64 v6, v8, v6, s[10:11]
	v_cndmask_b32_e64 v7, v14, v7, s[10:11]
	v_cmp_gt_i32_e32 vcc, s2, v126
	s_waitcnt lgkmcnt(1)
	v_add_f32_e32 v6, v6, v15
	s_waitcnt lgkmcnt(0)
	v_add_f32_e32 v7, v7, v16
	v_cndmask_b32_e64 v8, v6, v7, s[12:13]
	s_nop 1
	v_mov_b32_dpp v8, v8 quad_perm:[2,3,0,1] row_mask:0xf bank_mask:0xf
	v_cndmask_b32_e64 v6, v7, v6, s[12:13]
	s_and_b64 s[28:29], s[14:15], vcc
	s_waitcnt lgkmcnt(0)
	v_add_f32_e32 v6, v6, v8
	s_nop 1
	v_mov_b32_dpp v7, v6 row_shl:4 row_mask:0xf bank_mask:0x5
	v_mov_b32_dpp v7, v6 row_shr:4 row_mask:0xf bank_mask:0xa
	s_waitcnt lgkmcnt(0)
	v_add_f32_e32 v6, v6, v7
	s_nop 1
	v_mov_b32_dpp v7, v6 row_ror:8 row_mask:0xf bank_mask:0xf
	s_and_saveexec_b64 s[24:25], s[28:29]
	s_cbranch_execz .LBB0_1593
	v_mov_b32_e32 v8, 0xff800000
	s_and_saveexec_b64 s[28:29], s[66:67]
	s_cbranch_execz .LBB0_1592
	v_cmp_lt_i32_e32 vcc, 15, v9
	s_and_saveexec_b64 s[82:83], vcc
	s_xor_b64 s[82:83], exec, s[82:83]
	s_cbranch_execz .LBB0_1589
	v_cmp_lt_u32_e32 vcc, 20, v9
	s_nop 1
	v_cndmask_b32_e64 v8, 0, 1, vcc
	v_cmp_lt_u32_e32 vcc, 45, v9
	s_nop 1
	v_cndmask_b32_e64 v14, 0, 1, vcc
	v_cmp_lt_u32_e32 vcc, s86, v9
	s_nop 1
	v_cndmask_b32_e64 v15, 0, 1, vcc
	v_cmp_lt_u32_e32 vcc, s88, v9
	s_nop 1
	v_cndmask_b32_e64 v16, 0, 1, vcc
	v_cmp_lt_u32_e32 vcc, s90, v9
	s_nop 1
	v_cndmask_b32_e64 v17, 0, 1, vcc
	v_cmp_lt_u32_e32 vcc, s92, v9
	s_nop 1
	v_cndmask_b32_e64 v18, 0, 1, vcc
	v_cmp_lt_u32_e32 vcc, s94, v9
	s_nop 1
	v_cndmask_b32_e64 v19, 0, 1, vcc
	v_cmp_lt_u32_e32 vcc, 26, v9
	s_nop 1
	v_cndmask_b32_e64 v20, 16, 17, vcc
	v_cmp_lt_u32_e32 vcc, 34, v9
	s_nop 1
	v_addc_co_u32_e32 v8, vcc, v20, v8, vcc
	v_cmp_lt_u32_e32 vcc, 58, v9
	s_nop 1
	v_addc_co_u32_e32 v8, vcc, v8, v14, vcc
	v_cmp_lt_u32_e32 vcc, s87, v9
	s_nop 1
	v_addc_co_u32_e32 v8, vcc, v8, v15, vcc
	v_cmp_lt_u32_e32 vcc, s89, v9
	s_nop 1
	v_addc_co_u32_e32 v8, vcc, v8, v16, vcc
	v_cmp_lt_u32_e32 vcc, s91, v9
	s_nop 1
	v_addc_co_u32_e32 v8, vcc, v8, v17, vcc
	v_cmp_lt_u32_e32 vcc, s93, v9
	s_nop 1
	v_addc_co_u32_e32 v8, vcc, v8, v18, vcc
	v_cmp_lt_u32_e32 vcc, s95, v9
	s_nop 1
	v_addc_co_u32_e32 v14, vcc, v8, v19, vcc

; DI int rel_bucket(int d) {
;     if (d < 16) return d < 0 ? 0 : d;
;     int b = 16;
;     b += (d >= 21) + (d >= 27) + (d >= 35) + (d >= 46) + (d >= 59) + (d >= 77) + (d >= 99) + (d >= 128) + (d >= 166) + (d >= 216) + (d >= 280) + (d >= 363) + (d >= 470) + (d >= 609) + (d >= 790);
;     return b;
; }
; DI void snsa_unit(const Args& a, LAS unsigned char* lds, int s, int g) {
;     ...
;             for (int u = 0; u < 8; ++u) { const int kk = k0 + 32 * u;
;                 float p0 = x[u].x * q4[0].x + x[u].y * q4[0].y + x[u].z * q4[0].z + x[u].w * q4[0].w, p1 = x[u].x * q4[1].x + x[u].y * q4[1].y + x[u].z * q4[1].z + x[u].w * q4[1].w;
;                 float p2 = x[u].x * q4[2].x + x[u].y * q4[2].y + x[u].z * q4[2].z + x[u].w * q4[2].w, p3 = x[u].x * q4[3].x + x[u].y * q4[3].y + x[u].z * q4[3].z + x[u].w * q4[3].w;
;                 const bool o1 = (c16 & 1) != 0, o2 = (c16 & 2) != 0;
;                 float ka = o1 ? p2 : p0, kb2 = o1 ? p3 : p1; const float sa = o1 ? p0 : p2, sb = o1 ? p1 : p3;
;                 ka += __shfl_xor(sa, 1); kb2 += __shfl_xor(sb, 1);
;                 float e = o2 ? kb2 : ka; const float f = o2 ? ka : kb2;
;                 e += __shfl_xor(f, 2); e += __shfl_xor(e, 4); e += __shfl_xor(e, 8);
;                 if (c16 < 4 && kk < nkeys) SC[myh * 1024 + kk] = valid[u] ? e + rbias[rel_bucket(dist[u]) * 8 + g * 4 + myh] * LOG2E : -INFINITY; }
.LBB0_1593:
	s_or_b64 exec, exec, s[24:25]
	v_mul_f32_e32 v6, v23, v55
	s_waitcnt lgkmcnt(0)
	v_mul_f32_e32 v7, v27, v55
	v_mul_f32_e32 v8, v31, v55
	v_mul_f32_e32 v9, v35, v55
	v_fmac_f32_e32 v6, v22, v54
	v_fmac_f32_e32 v7, v26, v54
	v_fmac_f32_e32 v8, v30, v54
	v_fmac_f32_e32 v9, v34, v54
	v_fmac_f32_e32 v6, v24, v56
	v_fmac_f32_e32 v7, v28, v56
	v_fmac_f32_e32 v8, v32, v56
	v_fmac_f32_e32 v9, v36, v56
	v_fmac_f32_e32 v6, v25, v57
	v_fmac_f32_e32 v7, v29, v57
	v_fmac_f32_e32 v8, v33, v57
	v_fmac_f32_e32 v9, v37, v57
	v_cndmask_b32_e64 v14, v6, v8, s[10:11]
	v_cndmask_b32_e64 v15, v7, v9, s[10:11]
	s_nop 1
	v_mov_b32_dpp v14, v14 quad_perm:[1,0,3,2] row_mask:0xf bank_mask:0xf
	s_nop 1
	v_mov_b32_dpp v15, v15 quad_perm:[1,0,3,2] row_mask:0xf bank_mask:0xf
	v_cndmask_b32_e64 v6, v8, v6, s[10:11]
	v_cndmask_b32_e64 v7, v9, v7, s[10:11]
	v_cmp_gt_i32_e32 vcc, s2, v127
	s_waitcnt lgkmcnt(1)
	v_add_f32_e32 v6, v6, v14
	s_waitcnt lgkmcnt(0)
	v_add_f32_e32 v7, v7, v15
	v_cndmask_b32_e64 v8, v6, v7, s[12:13]
	s_nop 1
	v_mov_b32_dpp v8, v8 quad_perm:[2,3,0,1] row_mask:0xf bank_mask:0xf
	v_cndmask_b32_e64 v6, v7, v6, s[12:13]
	s_and_b64 s[28:29], s[14:15], vcc
	s_waitcnt lgkmcnt(0)
	v_add_f32_e32 v6, v6, v8
	s_nop 1
	v_mov_b32_dpp v7, v6 row_shl:4 row_mask:0xf bank_mask:0x5
	v_mov_b32_dpp v7, v6 row_shr:4 row_mask:0xf bank_mask:0xa
	s_waitcnt lgkmcnt(0)
	v_add_f32_e32 v6, v6, v7
	s_nop 1
	v_mov_b32_dpp v7, v6 row_ror:8 row_mask:0xf bank_mask:0xf
	s_and_saveexec_b64 s[24:25], s[28:29]
	s_cbranch_execz .LBB0_1601
	v_mov_b32_e32 v8, 0xff800000
	s_and_saveexec_b64 s[28:29], s[68:69]
	s_cbranch_execz .LBB0_1600
	v_cmp_lt_i32_e32 vcc, 15, v10
	s_and_saveexec_b64 s[82:83], vcc
	s_xor_b64 s[82:83], exec, s[82:83]
	s_cbranch_execz .LBB0_1597
	v_cmp_lt_u32_e32 vcc, 20, v10
	s_nop 1
	v_cndmask_b32_e64 v8, 0, 1, vcc
	v_cmp_lt_u32_e32 vcc, 45, v10
	s_nop 1
	v_cndmask_b32_e64 v9, 0, 1, vcc
	v_cmp_lt_u32_e32 vcc, s86, v10
	s_nop 1
	v_cndmask_b32_e64 v14, 0, 1, vcc
	v_cmp_lt_u32_e32 vcc, s88, v10
	s_nop 1
	v_cndmask_b32_e64 v15, 0, 1, vcc
	v_cmp_lt_u32_e32 vcc, s90, v10
	s_nop 1
	v_cndmask_b32_e64 v16, 0, 1, vcc
	v_cmp_lt_u32_e32 vcc, s92, v10
	s_nop 1
	v_cndmask_b32_e64 v17, 0, 1, vcc
	v_cmp_lt_u32_e32 vcc, s94, v10
	s_nop 1
	v_cndmask_b32_e64 v18, 0, 1, vcc
	v_cmp_lt_u32_e32 vcc, 26, v10
	s_nop 1
	v_cndmask_b32_e64 v19, 16, 17, vcc
	v_cmp_lt_u32_e32 vcc, 34, v10
	s_nop 1
	v_addc_co_u32_e32 v8, vcc, v19, v8, vcc
	v_cmp_lt_u32_e32 vcc, 58, v10
	s_nop 1
	v_addc_co_u32_e32 v8, vcc, v8, v9, vcc
	v_cmp_lt_u32_e32 vcc, s87, v10
	s_nop 1
	v_addc_co_u32_e32 v8, vcc, v8, v14, vcc
	v_cmp_lt_u32_e32 vcc, s89, v10
	s_nop 1
	v_addc_co_u32_e32 v8, vcc, v8, v15, vcc
	v_cmp_lt_u32_e32 vcc, s91, v10
	s_nop 1
	v_addc_co_u32_e32 v8, vcc, v8, v16, vcc
	v_cmp_lt_u32_e32 vcc, s93, v10
	s_nop 1
	v_addc_co_u32_e32 v8, vcc, v8, v17, vcc
	v_cmp_lt_u32_e32 vcc, s95, v10
	s_nop 1
	v_addc_co_u32_e32 v9, vcc, v8, v18, vcc

; DI int rel_bucket(int d) {
;     if (d < 16) return d < 0 ? 0 : d;
;     int b = 16;
;     b += (d >= 21) + (d >= 27) + (d >= 35) + (d >= 46) + (d >= 59) + (d >= 77) + (d >= 99) + (d >= 128) + (d >= 166) + (d >= 216) + (d >= 280) + (d >= 363) + (d >= 470) + (d >= 609) + (d >= 790);
;     return b;
; }
; DI void snsa_unit(const Args& a, LAS unsigned char* lds, int s, int g) {
;     ...
;             for (int u = 0; u < 8; ++u) { const int kk = k0 + 32 * u;
;                 float p0 = x[u].x * q4[0].x + x[u].y * q4[0].y + x[u].z * q4[0].z + x[u].w * q4[0].w, p1 = x[u].x * q4[1].x + x[u].y * q4[1].y + x[u].z * q4[1].z + x[u].w * q4[1].w;
;                 float p2 = x[u].x * q4[2].x + x[u].y * q4[2].y + x[u].z * q4[2].z + x[u].w * q4[2].w, p3 = x[u].x * q4[3].x + x[u].y * q4[3].y + x[u].z * q4[3].z + x[u].w * q4[3].w;
;                 const bool o1 = (c16 & 1) != 0, o2 = (c16 & 2) != 0;
;                 float ka = o1 ? p2 : p0, kb2 = o1 ? p3 : p1; const float sa = o1 ? p0 : p2, sb = o1 ? p1 : p3;
;                 ka += __shfl_xor(sa, 1); kb2 += __shfl_xor(sb, 1);
;                 float e = o2 ? kb2 : ka; const float f = o2 ? ka : kb2;
;                 e += __shfl_xor(f, 2); e += __shfl_xor(e, 4); e += __shfl_xor(e, 8);
;                 if (c16 < 4 && kk < nkeys) SC[myh * 1024 + kk] = valid[u] ? e + rbias[rel_bucket(dist[u]) * 8 + g * 4 + myh] * LOG2E : -INFINITY; }
.LBB0_1601:
	s_or_b64 exec, exec, s[24:25]
	v_mul_f32_e32 v6, v23, v59
	s_waitcnt lgkmcnt(0)
	v_mul_f32_e32 v7, v27, v59
	v_mul_f32_e32 v8, v31, v59
	v_mul_f32_e32 v9, v35, v59
	v_fmac_f32_e32 v6, v22, v58
	v_fmac_f32_e32 v7, v26, v58
	v_fmac_f32_e32 v8, v30, v58
	v_fmac_f32_e32 v9, v34, v58
	v_fmac_f32_e32 v6, v24, v60
	v_fmac_f32_e32 v7, v28, v60
	v_fmac_f32_e32 v8, v32, v60
	v_fmac_f32_e32 v9, v36, v60
	v_fmac_f32_e32 v6, v25, v61
	v_fmac_f32_e32 v7, v29, v61
	v_fmac_f32_e32 v8, v33, v61
	v_fmac_f32_e32 v9, v37, v61
	v_cndmask_b32_e64 v10, v6, v8, s[10:11]
	v_cndmask_b32_e64 v14, v7, v9, s[10:11]
	s_nop 1
	v_mov_b32_dpp v10, v10 quad_perm:[1,0,3,2] row_mask:0xf bank_mask:0xf
	s_nop 1
	v_mov_b32_dpp v14, v14 quad_perm:[1,0,3,2] row_mask:0xf bank_mask:0xf
	v_cndmask_b32_e64 v6, v8, v6, s[10:11]
	v_cndmask_b32_e64 v7, v9, v7, s[10:11]
	v_cmp_gt_i32_e32 vcc, s2, v128
	s_waitcnt lgkmcnt(1)
	v_add_f32_e32 v6, v6, v10
	s_waitcnt lgkmcnt(0)
	v_add_f32_e32 v7, v7, v14
	v_cndmask_b32_e64 v8, v6, v7, s[12:13]
	s_nop 1
	v_mov_b32_dpp v8, v8 quad_perm:[2,3,0,1] row_mask:0xf bank_mask:0xf
	v_cndmask_b32_e64 v6, v7, v6, s[12:13]
	s_and_b64 s[28:29], s[14:15], vcc
	s_waitcnt lgkmcnt(0)
	v_add_f32_e32 v6, v6, v8
	s_nop 1
	v_mov_b32_dpp v7, v6 row_shl:4 row_mask:0xf bank_mask:0x5
	v_mov_b32_dpp v7, v6 row_shr:4 row_mask:0xf bank_mask:0xa
	s_waitcnt lgkmcnt(0)
	v_add_f32_e32 v6, v6, v7
	s_nop 1
	v_mov_b32_dpp v7, v6 row_ror:8 row_mask:0xf bank_mask:0xf
	s_and_saveexec_b64 s[24:25], s[28:29]
	s_cbranch_execz .LBB0_1609
	v_mov_b32_e32 v8, 0xff800000
	s_and_saveexec_b64 s[28:29], s[70:71]
	s_cbranch_execz .LBB0_1608
	v_cmp_lt_i32_e32 vcc, 15, v11
	s_and_saveexec_b64 s[82:83], vcc
	s_xor_b64 s[82:83], exec, s[82:83]
	s_cbranch_execz .LBB0_1605
	v_cmp_lt_u32_e32 vcc, 20, v11
	s_nop 1
	v_cndmask_b32_e64 v8, 0, 1, vcc
	v_cmp_lt_u32_e32 vcc, 45, v11
	s_nop 1
	v_cndmask_b32_e64 v9, 0, 1, vcc
	v_cmp_lt_u32_e32 vcc, s86, v11
	s_nop 1
	v_cndmask_b32_e64 v10, 0, 1, vcc
	v_cmp_lt_u32_e32 vcc, s88, v11
	s_nop 1
	v_cndmask_b32_e64 v14, 0, 1, vcc
	v_cmp_lt_u32_e32 vcc, s90, v11
	s_nop 1
	v_cndmask_b32_e64 v15, 0, 1, vcc
	v_cmp_lt_u32_e32 vcc, s92, v11
	s_nop 1
	v_cndmask_b32_e64 v16, 0, 1, vcc
	v_cmp_lt_u32_e32 vcc, s94, v11
	s_nop 1
	v_cndmask_b32_e64 v17, 0, 1, vcc
	v_cmp_lt_u32_e32 vcc, 26, v11
	s_nop 1
	v_cndmask_b32_e64 v18, 16, 17, vcc
	v_cmp_lt_u32_e32 vcc, 34, v11
	s_nop 1
	v_addc_co_u32_e32 v8, vcc, v18, v8, vcc
	v_cmp_lt_u32_e32 vcc, 58, v11
	s_nop 1
	v_addc_co_u32_e32 v8, vcc, v8, v9, vcc
	v_cmp_lt_u32_e32 vcc, s87, v11
	s_nop 1
	v_addc_co_u32_e32 v8, vcc, v8, v10, vcc
	v_cmp_lt_u32_e32 vcc, s89, v11
	s_nop 1
	v_addc_co_u32_e32 v8, vcc, v8, v14, vcc
	v_cmp_lt_u32_e32 vcc, s91, v11
	s_nop 1
	v_addc_co_u32_e32 v8, vcc, v8, v15, vcc
	v_cmp_lt_u32_e32 vcc, s93, v11
	s_nop 1
	v_addc_co_u32_e32 v8, vcc, v8, v16, vcc
	v_cmp_lt_u32_e32 vcc, s95, v11
	s_nop 1
	v_addc_co_u32_e32 v9, vcc, v8, v17, vcc

; DI int rel_bucket(int d) {
;     if (d < 16) return d < 0 ? 0 : d;
;     int b = 16;
;     b += (d >= 21) + (d >= 27) + (d >= 35) + (d >= 46) + (d >= 59) + (d >= 77) + (d >= 99) + (d >= 128) + (d >= 166) + (d >= 216) + (d >= 280) + (d >= 363) + (d >= 470) + (d >= 609) + (d >= 790);
;     return b;
; }
; DI void snsa_unit(const Args& a, LAS unsigned char* lds, int s, int g) {
;     ...
;             for (int u = 0; u < 8; ++u) { const int kk = k0 + 32 * u;
;                 float p0 = x[u].x * q4[0].x + x[u].y * q4[0].y + x[u].z * q4[0].z + x[u].w * q4[0].w, p1 = x[u].x * q4[1].x + x[u].y * q4[1].y + x[u].z * q4[1].z + x[u].w * q4[1].w;
;                 float p2 = x[u].x * q4[2].x + x[u].y * q4[2].y + x[u].z * q4[2].z + x[u].w * q4[2].w, p3 = x[u].x * q4[3].x + x[u].y * q4[3].y + x[u].z * q4[3].z + x[u].w * q4[3].w;
;                 const bool o1 = (c16 & 1) != 0, o2 = (c16 & 2) != 0;
;                 float ka = o1 ? p2 : p0, kb2 = o1 ? p3 : p1; const float sa = o1 ? p0 : p2, sb = o1 ? p1 : p3;
;                 ka += __shfl_xor(sa, 1); kb2 += __shfl_xor(sb, 1);
;                 float e = o2 ? kb2 : ka; const float f = o2 ? ka : kb2;
;                 e += __shfl_xor(f, 2); e += __shfl_xor(e, 4); e += __shfl_xor(e, 8);
;                 if (c16 < 4 && kk < nkeys) SC[myh * 1024 + kk] = valid[u] ? e + rbias[rel_bucket(dist[u]) * 8 + g * 4 + myh] * LOG2E : -INFINITY; }
.LBB0_1609:
	s_or_b64 exec, exec, s[24:25]
	v_mul_f32_e32 v6, v23, v63
	s_waitcnt lgkmcnt(0)
	v_mul_f32_e32 v7, v27, v63
	v_mul_f32_e32 v8, v31, v63
	v_mul_f32_e32 v9, v35, v63
	v_fmac_f32_e32 v6, v22, v62
	v_fmac_f32_e32 v7, v26, v62
	v_fmac_f32_e32 v8, v30, v62
	v_fmac_f32_e32 v9, v34, v62
	v_fmac_f32_e32 v6, v24, v64
	v_fmac_f32_e32 v7, v28, v64
	v_fmac_f32_e32 v8, v32, v64
	v_fmac_f32_e32 v9, v36, v64
	v_fmac_f32_e32 v6, v25, v65
	v_fmac_f32_e32 v7, v29, v65
	v_fmac_f32_e32 v8, v33, v65
	v_fmac_f32_e32 v9, v37, v65
	v_cndmask_b32_e64 v10, v6, v8, s[10:11]
	v_cndmask_b32_e64 v11, v7, v9, s[10:11]
	s_nop 1
	v_mov_b32_dpp v10, v10 quad_perm:[1,0,3,2] row_mask:0xf bank_mask:0xf
	s_nop 1
	v_mov_b32_dpp v11, v11 quad_perm:[1,0,3,2] row_mask:0xf bank_mask:0xf
	v_cndmask_b32_e64 v6, v8, v6, s[10:11]
	v_cndmask_b32_e64 v7, v9, v7, s[10:11]
	v_cmp_gt_i32_e32 vcc, s2, v129
	s_waitcnt lgkmcnt(1)
	v_add_f32_e32 v6, v6, v10
	s_waitcnt lgkmcnt(0)
	v_add_f32_e32 v7, v7, v11
	v_cndmask_b32_e64 v8, v6, v7, s[12:13]
	s_nop 1
	v_mov_b32_dpp v8, v8 quad_perm:[2,3,0,1] row_mask:0xf bank_mask:0xf
	v_cndmask_b32_e64 v6, v7, v6, s[12:13]
	s_and_b64 s[28:29], s[14:15], vcc
	s_waitcnt lgkmcnt(0)
	v_add_f32_e32 v6, v6, v8
	s_nop 1
	v_mov_b32_dpp v7, v6 row_shl:4 row_mask:0xf bank_mask:0x5
	v_mov_b32_dpp v7, v6 row_shr:4 row_mask:0xf bank_mask:0xa
	s_waitcnt lgkmcnt(0)
	v_add_f32_e32 v6, v6, v7
	s_nop 1
	v_mov_b32_dpp v7, v6 row_ror:8 row_mask:0xf bank_mask:0xf
	s_and_saveexec_b64 s[24:25], s[28:29]
	s_cbranch_execz .LBB0_1617
	v_mov_b32_e32 v8, 0xff800000
	s_and_saveexec_b64 s[28:29], s[78:79]
	s_cbranch_execz .LBB0_1616
	v_cmp_lt_i32_e32 vcc, 15, v12
	s_and_saveexec_b64 s[82:83], vcc
	s_xor_b64 s[82:83], exec, s[82:83]
	s_cbranch_execz .LBB0_1613
	v_cmp_lt_u32_e32 vcc, 20, v12
	s_nop 1
	v_cndmask_b32_e64 v8, 0, 1, vcc
	v_cmp_lt_u32_e32 vcc, 45, v12
	s_nop 1
	v_cndmask_b32_e64 v9, 0, 1, vcc
	v_cmp_lt_u32_e32 vcc, s86, v12
	s_nop 1
	v_cndmask_b32_e64 v10, 0, 1, vcc
	v_cmp_lt_u32_e32 vcc, s88, v12
	s_nop 1
	v_cndmask_b32_e64 v11, 0, 1, vcc
	v_cmp_lt_u32_e32 vcc, s90, v12
	s_nop 1
	v_cndmask_b32_e64 v14, 0, 1, vcc
	v_cmp_lt_u32_e32 vcc, s92, v12
	s_nop 1
	v_cndmask_b32_e64 v15, 0, 1, vcc
	v_cmp_lt_u32_e32 vcc, s94, v12
	s_nop 1
	v_cndmask_b32_e64 v16, 0, 1, vcc
	v_cmp_lt_u32_e32 vcc, 26, v12
	s_nop 1
	v_cndmask_b32_e64 v17, 16, 17, vcc
	v_cmp_lt_u32_e32 vcc, 34, v12
	s_nop 1
	v_addc_co_u32_e32 v8, vcc, v17, v8, vcc
	v_cmp_lt_u32_e32 vcc, 58, v12
	s_nop 1
	v_addc_co_u32_e32 v8, vcc, v8, v9, vcc
	v_cmp_lt_u32_e32 vcc, s87, v12
	s_nop 1
	v_addc_co_u32_e32 v8, vcc, v8, v10, vcc
	v_cmp_lt_u32_e32 vcc, s89, v12
	s_nop 1
	v_addc_co_u32_e32 v8, vcc, v8, v11, vcc
	v_cmp_lt_u32_e32 vcc, s91, v12
	s_nop 1
	v_addc_co_u32_e32 v8, vcc, v8, v14, vcc
	v_cmp_lt_u32_e32 vcc, s93, v12
	s_nop 1
	v_addc_co_u32_e32 v8, vcc, v8, v15, vcc
	v_cmp_lt_u32_e32 vcc, s95, v12
	s_nop 1
	v_addc_co_u32_e32 v9, vcc, v8, v16, vcc

; DI int rel_bucket(int d) {
;     if (d < 16) return d < 0 ? 0 : d;
;     int b = 16;
;     b += (d >= 21) + (d >= 27) + (d >= 35) + (d >= 46) + (d >= 59) + (d >= 77) + (d >= 99) + (d >= 128) + (d >= 166) + (d >= 216) + (d >= 280) + (d >= 363) + (d >= 470) + (d >= 609) + (d >= 790);
;     return b;
; }
; DI void snsa_unit(const Args& a, LAS unsigned char* lds, int s, int g) {
;     ...
;             for (int u = 0; u < 8; ++u) { const int kk = k0 + 32 * u;
;                 float p0 = x[u].x * q4[0].x + x[u].y * q4[0].y + x[u].z * q4[0].z + x[u].w * q4[0].w, p1 = x[u].x * q4[1].x + x[u].y * q4[1].y + x[u].z * q4[1].z + x[u].w * q4[1].w;
;                 float p2 = x[u].x * q4[2].x + x[u].y * q4[2].y + x[u].z * q4[2].z + x[u].w * q4[2].w, p3 = x[u].x * q4[3].x + x[u].y * q4[3].y + x[u].z * q4[3].z + x[u].w * q4[3].w;
;                 const bool o1 = (c16 & 1) != 0, o2 = (c16 & 2) != 0;
;                 float ka = o1 ? p2 : p0, kb2 = o1 ? p3 : p1; const float sa = o1 ? p0 : p2, sb = o1 ? p1 : p3;
;                 ka += __shfl_xor(sa, 1); kb2 += __shfl_xor(sb, 1);
;                 float e = o2 ? kb2 : ka; const float f = o2 ? ka : kb2;
;                 e += __shfl_xor(f, 2); e += __shfl_xor(e, 4); e += __shfl_xor(e, 8);
;                 if (c16 < 4 && kk < nkeys) SC[myh * 1024 + kk] = valid[u] ? e + rbias[rel_bucket(dist[u]) * 8 + g * 4 + myh] * LOG2E : -INFINITY; }
.LBB0_1617:
	s_or_b64 exec, exec, s[24:25]
	v_mul_f32_e32 v6, v23, v67
	s_waitcnt lgkmcnt(0)
	v_mul_f32_e32 v7, v27, v67
	v_mul_f32_e32 v8, v31, v67
	v_mul_f32_e32 v9, v35, v67
	v_fmac_f32_e32 v6, v22, v66
	v_fmac_f32_e32 v7, v26, v66
	v_fmac_f32_e32 v8, v30, v66
	v_fmac_f32_e32 v9, v34, v66
	v_fmac_f32_e32 v6, v24, v68
	v_fmac_f32_e32 v7, v28, v68
	v_fmac_f32_e32 v8, v32, v68
	v_fmac_f32_e32 v9, v36, v68
	v_fmac_f32_e32 v6, v25, v69
	v_fmac_f32_e32 v7, v29, v69
	v_fmac_f32_e32 v8, v33, v69
	v_fmac_f32_e32 v9, v37, v69
	v_cndmask_b32_e64 v10, v6, v8, s[10:11]
	v_cndmask_b32_e64 v11, v7, v9, s[10:11]
	s_nop 1
	v_mov_b32_dpp v10, v10 quad_perm:[1,0,3,2] row_mask:0xf bank_mask:0xf
	s_nop 1
	v_mov_b32_dpp v11, v11 quad_perm:[1,0,3,2] row_mask:0xf bank_mask:0xf
	v_cndmask_b32_e64 v6, v8, v6, s[10:11]
	v_cndmask_b32_e64 v7, v9, v7, s[10:11]
	v_cmp_gt_i32_e32 vcc, s2, v130
	s_waitcnt lgkmcnt(1)
	v_add_f32_e32 v6, v6, v10
	s_waitcnt lgkmcnt(0)
	v_add_f32_e32 v7, v7, v11
	v_cndmask_b32_e64 v8, v6, v7, s[12:13]
	s_nop 1
	v_mov_b32_dpp v8, v8 quad_perm:[2,3,0,1] row_mask:0xf bank_mask:0xf
	v_cndmask_b32_e64 v6, v7, v6, s[12:13]
	s_and_b64 s[28:29], s[14:15], vcc
	s_waitcnt lgkmcnt(0)
	v_add_f32_e32 v6, v6, v8
	s_nop 1
	v_mov_b32_dpp v7, v6 row_shl:4 row_mask:0xf bank_mask:0x5
	v_mov_b32_dpp v7, v6 row_shr:4 row_mask:0xf bank_mask:0xa
	s_waitcnt lgkmcnt(0)
	v_add_f32_e32 v14, v6, v7
	s_nop 1
	v_mov_b32_dpp v15, v14 row_ror:8 row_mask:0xf bank_mask:0xf
	s_and_saveexec_b64 s[24:25], s[28:29]
	s_cbranch_execz .LBB0_1464
	v_mov_b32_e32 v6, 0xff800000
	s_and_saveexec_b64 s[28:29], s[26:27]
	s_cbranch_execz .LBB0_1463
	v_cmp_lt_i32_e32 vcc, 15, v13
	s_and_saveexec_b64 s[82:83], vcc
	s_xor_b64 s[82:83], exec, s[82:83]
	s_cbranch_execz .LBB0_1621
	v_cmp_lt_u32_e32 vcc, 20, v13
	s_nop 1
	v_cndmask_b32_e64 v6, 0, 1, vcc
	v_cmp_lt_u32_e32 vcc, 45, v13
	s_nop 1
	v_cndmask_b32_e64 v7, 0, 1, vcc
	v_cmp_lt_u32_e32 vcc, s86, v13
	s_nop 1
	v_cndmask_b32_e64 v8, 0, 1, vcc
	v_cmp_lt_u32_e32 vcc, s88, v13
	s_nop 1
	v_cndmask_b32_e64 v9, 0, 1, vcc
	v_cmp_lt_u32_e32 vcc, s90, v13
	s_nop 1
	v_cndmask_b32_e64 v10, 0, 1, vcc
	v_cmp_lt_u32_e32 vcc, s92, v13
	s_nop 1
	v_cndmask_b32_e64 v11, 0, 1, vcc
	v_cmp_lt_u32_e32 vcc, s94, v13
	s_nop 1
	v_cndmask_b32_e64 v12, 0, 1, vcc
	v_cmp_lt_u32_e32 vcc, 26, v13
	s_nop 1
	v_cndmask_b32_e64 v16, 16, 17, vcc
	v_cmp_lt_u32_e32 vcc, 34, v13
	s_nop 1
	v_addc_co_u32_e32 v6, vcc, v16, v6, vcc
	v_cmp_lt_u32_e32 vcc, 58, v13
	s_nop 1
	v_addc_co_u32_e32 v6, vcc, v6, v7, vcc
	v_cmp_lt_u32_e32 vcc, s87, v13
	s_nop 1
	v_addc_co_u32_e32 v6, vcc, v6, v8, vcc
	v_cmp_lt_u32_e32 vcc, s89, v13
	s_nop 1
	v_addc_co_u32_e32 v6, vcc, v6, v9, vcc
	v_cmp_lt_u32_e32 vcc, s91, v13
	s_nop 1
	v_addc_co_u32_e32 v6, vcc, v6, v10, vcc
	v_cmp_lt_u32_e32 vcc, s93, v13
	s_nop 1
	v_addc_co_u32_e32 v6, vcc, v6, v11, vcc
	v_cmp_lt_u32_e32 vcc, s95, v13
	s_nop 1
	v_addc_co_u32_e32 v16, vcc, v6, v12, vcc
